# v72 + K/V (and FoX bias) LDS-DMA addresses in both attention phases: 64-bit v_lshl_add_u64 replaced by v_lshlrev_b32 + SGPR-base global_load_lds
# speedup vs baseline: 1.0136x; 1.0066x over previous
.LBB0_718:
	s_lshl_b32 s72, s0, 4
	s_lshr_b32 s1, s9, 5
	s_and_b32 s11, s6, 31
	s_or_b32 s16, s72, s3
	s_lshl_b32 s10, s11, 8
	s_and_b32 s1, s1, 15
	s_lshl_b32 s94, s11, 18
	s_add_i32 s15, s2, 0x100
	s_and_b32 s11, s7, 0xffffffc0
	s_ashr_i32 s7, s7, 31
	s_ashr_i32 s17, s16, 31
	s_lshl_b32 s5, s1, 6
	s_add_i32 s94, s94, 0x40000
	s_add_i32 s18, s92, s2
	s_lshr_b32 s7, s7, 29
	s_or_b32 s19, s20, 0x4000000
	s_lshr_b32 s95, s15, 7
	s_or_b32 s15, s20, 0x6000000
	s_lshl_b64 s[16:17], s[16:17], 15
	v_readlane_b32 s3, v249, 48
	s_add_u32 s16, s3, s16
	v_readlane_b32 s3, v249, 49
	s_addc_u32 s17, s3, s17
	s_lshr_b32 s33, s18, 6
	s_lshl_b32 s2, s2, 2
	v_writelane_b32 v248, s20, 6
	s_add_u32 s20, s16, s2
	s_addc_u32 s21, s17, 0
	s_lshl_b64 s[2:3], s[92:93], 2
	s_add_u32 s2, s20, s2
	s_addc_u32 s3, s21, s3
	v_lshlrev_b32_e32 v0, 2, v104
	global_load_dword v12, v0, s[2:3]
	v_or_b32_e32 v0, s11, v102
	v_add_u32_e32 v2, s7, v0
	v_ashrrev_i32_e32 v13, 3, v2
	v_and_b32_e32 v2, -8, v2
	v_sub_u32_e32 v14, v0, v2
	v_add_u32_e32 v0, 0x200, v0
	v_ashrrev_i32_e32 v4, 31, v0
	v_lshrrev_b32_e32 v2, 1, v13
	v_lshrrev_b32_e32 v4, 29, v4
	v_bitop3_b32 v15, v2, 7, v222 bitop3:0x48
	s_mov_b32 s2, 0x1ffffff8
	v_add_u32_e32 v4, v0, v4
	v_lshlrev_b32_e32 v6, 1, v13
	v_and_or_b32 v2, v14, s2, v15
	v_ashrrev_i32_e32 v16, 3, v4
	v_bitop3_b32 v6, v14, v6, 4 bitop3:0x78
	v_lshlrev_b32_e32 v2, 3, v2
	s_waitcnt lgkmcnt(0)
	v_add_lshl_u32 v3, v13, s14, 10
	v_and_b32_e32 v17, -8, v4
	v_lshrrev_b32_e32 v4, 1, v16
	v_lshlrev_b32_e32 v19, 3, v6
	v_add3_u32 v2, s19, v3, v2
	v_sub_u32_e32 v0, v0, v17
	v_bitop3_b32 v18, v4, 7, v222 bitop3:0x48
	v_add3_u32 v6, s15, v19, v3
	v_lshlrev_b32_e32 v3, 1, v16
	v_and_or_b32 v4, v0, s2, v18
	v_bitop3_b32 v0, v0, v3, 4 bitop3:0x78
	s_lshl_b32 s2, s22, 10
	v_lshlrev_b32_e32 v4, 3, v4
	v_add_lshl_u32 v5, v16, s14, 10
	v_lshlrev_b32_e32 v20, 3, v0
	s_add_i32 s3, s2, 0
	v_mov_b32_e32 v3, v1
	v_add3_u32 v4, s19, v5, v4
	v_add3_u32 v8, s15, v20, v5
	v_lshl_add_u64 v[2:3], v[2:3], 1, s[84:85]
	s_mov_b32 m0, s3
	v_mov_b32_e32 v5, v1
	global_load_lds_dwordx4 v[2:3], off
	v_lshlrev_b32_e32 v2, 1, v4
	s_add_i32 m0, s3, 0x2000
	v_mov_b32_e32 v7, v1
	global_load_lds_dwordx4 v2, s[84:85]
	s_add_i32 m0, s3, 0x4000
	v_lshlrev_b32_e32 v2, 1, v6
	v_mov_b32_e32 v9, v1
	s_lshl_b32 s7, s22, 9
	v_lshlrev_b32_e32 v0, 2, v102
	global_load_lds_dwordx4 v2, s[84:85]
	v_lshlrev_b32_e32 v2, 1, v8
	s_add_i32 m0, s3, 0x6000
	s_add_i32 s14, s7, 0
	v_lshl_add_u64 v[10:11], s[16:17], 0, v[0:1]
	global_load_lds_dwordx4 v2, s[84:85]
	s_add_i32 m0, s14, 0x8000
	v_lshl_add_u64 v[2:3], v[10:11], 0, s[12:13]
	global_load_lds_dword v0, s[16:17]
	s_add_i32 m0, s14, 0x8100
	s_lshl_b32 s4, s4, 2
	global_load_lds_dword v[2:3], off
	s_add_i32 s4, s4, 0
	s_add_i32 s4, s4, 0x1b000
	v_mov_b32_e32 v0, s4
	s_waitcnt vmcnt(0) lgkmcnt(0)
	s_barrier
	s_waitcnt vmcnt(0)
	ds_read_b32 v0, v0
	s_and_b32 s4, s18, 0x7fffffc0
	v_or_b32_e32 v51, s18, v104
	v_writelane_b32 v248, s22, 9
	s_lshl_b32 s0, s0, 23
	s_waitcnt lgkmcnt(0)
	v_add_f32_e32 v113, v12, v0
	v_or_b32_e32 v0, s4, v130
	v_or_b32_e32 v2, 32, v0
	v_cmp_gt_u32_e64 s[16:17], v2, v51
	v_or_b32_e32 v2, 33, v0
	v_cmp_gt_u32_e64 s[20:21], v2, v51
	v_or_b32_e32 v2, 2, v0
	v_cmp_gt_u32_e64 s[22:23], v2, v51
	v_or_b32_e32 v2, 34, v0
	v_cmp_gt_u32_e64 s[24:25], v2, v51
	v_or_b32_e32 v2, 3, v0
	v_cmp_gt_u32_e64 s[26:27], v2, v51
	v_or_b32_e32 v2, 35, v0
	v_cmp_gt_u32_e64 s[28:29], v2, v51
	v_or_b32_e32 v2, 8, v0
	v_cmp_gt_u32_e64 s[30:31], v2, v51
	v_or_b32_e32 v2, 40, v0
	v_cmp_gt_u32_e64 s[34:35], v2, v51
	v_or_b32_e32 v2, 9, v0
	v_cmp_gt_u32_e64 s[36:37], v2, v51
	v_or_b32_e32 v2, 41, v0
	v_cmp_gt_u32_e64 s[38:39], v2, v51
	v_or_b32_e32 v2, 10, v0
	v_cmp_gt_u32_e64 s[40:41], v2, v51
	v_or_b32_e32 v2, 42, v0
	v_cmp_gt_u32_e64 s[42:43], v2, v51
	v_or_b32_e32 v2, 11, v0
	v_cmp_gt_u32_e64 s[44:45], v2, v51
	v_or_b32_e32 v2, 43, v0
	v_cmp_gt_u32_e64 s[46:47], v2, v51
	v_or_b32_e32 v2, 16, v0
	v_cmp_gt_u32_e64 s[48:49], v2, v51
	v_or_b32_e32 v2, 48, v0
	v_cmp_gt_u32_e64 s[50:51], v2, v51
	v_or_b32_e32 v2, 17, v0
	v_cmp_gt_u32_e64 s[52:53], v2, v51
	v_or_b32_e32 v2, 49, v0
	v_cmp_gt_u32_e64 s[54:55], v2, v51
	v_or_b32_e32 v2, 18, v0
	v_cmp_gt_u32_e64 s[56:57], v2, v51
	v_or_b32_e32 v2, 50, v0
	v_cmp_gt_u32_e64 s[58:59], v2, v51
	v_or_b32_e32 v2, 19, v0
	v_cmp_gt_u32_e64 s[60:61], v2, v51
	v_or_b32_e32 v2, 51, v0
	v_cmp_gt_u32_e64 s[62:63], v2, v51
	v_or_b32_e32 v2, 24, v0
	v_cmp_gt_u32_e64 s[64:65], v2, v51
	v_or_b32_e32 v2, 56, v0
	v_cmp_gt_u32_e64 s[66:67], v2, v51
	v_or_b32_e32 v2, 25, v0
	v_cmp_gt_u32_e64 s[14:15], v0, v51
	v_cmp_lt_u32_e64 s[18:19], v0, v51
	v_cmp_gt_u32_e64 s[68:69], v2, v51
	v_or_b32_e32 v2, 57, v0
	v_or_b32_e32 v52, 26, v0
	v_or_b32_e32 v53, 58, v0
	v_or_b32_e32 v54, 27, v0
	v_or_b32_e32 v55, 59, v0
	s_add_i32 s4, s0, 0x6020000
	v_lshlrev_b32_e32 v0, 10, v16
	v_cmp_gt_u32_e64 s[70:71], v2, v51
	v_add_u32_e32 v2, s4, v0
	v_lshlrev_b32_e32 v3, 10, v13
	v_add_u32_e32 v4, s4, v3
	v_or_b32_e32 v2, s5, v2
	v_add_u32_e32 v5, s11, v134
	v_add_u32_e32 v115, v2, v20
	v_or_b32_e32 v2, s5, v4
	v_add_u32_e32 v117, v2, v19
	v_sub_u32_e32 v2, v5, v17
	s_add_i32 s0, s0, 0x4020000
	v_lshlrev_b32_e32 v2, 3, v2
	v_add_u32_e32 v0, s0, v0
	v_and_b32_e32 v2, 0xffffffc0, v2
	v_add3_u32 v0, v0, v2, s5
	v_lshlrev_b32_e32 v2, 3, v14
	v_lshl_or_b32 v119, v18, 3, v0
	v_add_u32_e32 v0, s0, v3
	v_and_b32_e32 v2, 0xffffffc0, v2
	v_add3_u32 v0, v0, v2, s5
	s_or_b32 s0, s72, s1
	s_add_i32 s10, s10, s92
	v_lshl_or_b32 v121, v15, 3, v0
	s_ashr_i32 s1, s0, 31
	v_mov_b32_e32 v2, v1
	v_mov_b32_e32 v3, v1
	v_mov_b32_e32 v4, v1
	v_mov_b32_e32 v5, v1
	v_mov_b32_e32 v6, v1
	v_mov_b32_e32 v8, v1
	v_mov_b32_e32 v10, v1
	v_mov_b32_e32 v11, v1
	v_mov_b32_e32 v12, v1
	v_mov_b32_e32 v13, v1
	v_mov_b32_e32 v14, v1
	v_mov_b32_e32 v15, v1
	v_mov_b32_e32 v16, v1
	v_mov_b32_e32 v17, v1
	v_mov_b32_e32 v18, v1
	v_mov_b32_e32 v19, v1
	v_mov_b32_e32 v20, v1
	v_mov_b32_e32 v21, v1
	v_mov_b32_e32 v22, v1
	v_mov_b32_e32 v23, v1
	v_mov_b32_e32 v24, v1
	v_mov_b32_e32 v25, v1
	v_mov_b32_e32 v26, v1
	v_mov_b32_e32 v27, v1
	v_mov_b32_e32 v28, v1
	v_mov_b32_e32 v29, v1
	v_mov_b32_e32 v30, v1
	v_mov_b32_e32 v31, v1
	s_lshr_b32 s92, s10, 6
	s_lshl_b64 s[0:1], s[0:1], 15
	v_mov_b32_e32 v0, v1
	v_mov_b64_e32 v[32:33], v[30:31]
	s_add_i32 s4, s92, -1
	v_lshl_add_u64 v[122:123], v[108:109], 0, s[0:1]
	s_mov_b32 s5, 0
	v_mov_b32_e32 v34, v1
	v_mov_b32_e32 v35, v1
	v_mov_b32_e32 v36, v1
	v_mov_b32_e32 v37, v1
	v_mov_b32_e32 v38, v1
	v_mov_b32_e32 v39, v1
	v_mov_b32_e32 v40, v1
	v_mov_b32_e32 v41, v1
	v_mov_b32_e32 v42, v1
	v_mov_b32_e32 v43, v1
	v_mov_b32_e32 v44, v1
	v_mov_b32_e32 v45, v1
	v_mov_b32_e32 v46, v1
	v_mov_b32_e32 v47, v1
	v_mov_b32_e32 v48, v1
	v_mov_b32_e32 v49, v1
	s_mov_b32 s90, 0x9000
	v_mov_b32_e32 v137, 0
	s_mov_b32 s91, 0
	s_mov_b32 s0, 0
	v_mov_b64_e32 v[30:31], v[28:29]
	v_mov_b64_e32 v[28:29], v[26:27]
	v_mov_b64_e32 v[26:27], v[24:25]
	v_mov_b64_e32 v[24:25], v[22:23]
	v_mov_b64_e32 v[22:23], v[20:21]
	v_mov_b64_e32 v[20:21], v[18:19]
	v_mov_b64_e32 v[18:19], v[16:17]
	v_mov_b64_e32 v[16:17], v[14:15]
	v_mov_b64_e32 v[14:15], v[12:13]
	v_mov_b64_e32 v[12:13], v[10:11]
	v_mov_b64_e32 v[10:11], v[8:9]
	v_mov_b64_e32 v[8:9], v[6:7]
	v_mov_b64_e32 v[6:7], v[4:5]
	v_mov_b64_e32 v[4:5], v[2:3]
	v_mov_b64_e32 v[2:3], v[0:1]
	s_mov_b32 s1, 0
	v_cmp_gt_u32_e64 s[72:73], v52, v51
	v_cmp_gt_u32_e64 s[74:75], v53, v51
	v_cmp_gt_u32_e64 s[76:77], v54, v51
	v_cmp_gt_u32_e64 s[78:79], v55, v51
	s_add_i32 s10, s1, 1
	s_cmp_ge_u32 s10, s95
	s_cbranch_scc1 .LBB0_720
.LBB0_719:
	s_add_i32 s11, s3, s90
	v_add_u32_e32 v0, s91, v121
	v_lshlrev_b32_e32 v138, 1, v0
	s_mov_b32 m0, s11
	v_add_u32_e32 v0, s91, v119
	global_load_lds_dwordx4 v138, s[84:85]
	s_add_i32 m0, s11, 0x2000
	s_add_i32 s11, s90, 0
	v_lshlrev_b32_e32 v138, 1, v0
	s_add_i32 s96, s11, s2
	v_add_u32_e32 v0, s91, v117
	global_load_lds_dwordx4 v138, s[84:85]
	s_add_i32 m0, s96, 0x4000
	v_lshlrev_b32_e32 v138, 1, v0
	v_add_u32_e32 v0, s91, v115
	global_load_lds_dwordx4 v138, s[84:85]
	v_lshlrev_b32_e32 v138, 1, v0
	s_add_i32 m0, s96, 0x6000
	s_add_i32 s11, s11, s7
	global_load_lds_dwordx4 v138, s[84:85]
	s_add_i32 m0, s11, 0x8000
	v_lshl_add_u64 v[138:139], v[122:123], 0, s[12:13]
	global_load_lds_dword v[122:123], off
	s_add_i32 m0, s11, 0x8100
	s_nop 0
	global_load_lds_dword v[138:139], off

.LBB0_748:
	s_add_i32 s0, s2, 0x100
	s_ashr_i32 s1, s3, 31
	v_readlane_b32 s66, v249, 62
	s_lshr_b32 s6, s1, 29
	s_lshr_b32 s72, s0, 7
	s_lshl_b32 s0, s66, 4
	v_readlane_b32 s1, v249, 60
	s_or_b32 s0, s0, s1
	s_ashr_i32 s1, s0, 31
	s_add_i32 s4, s76, s2
	s_and_b32 s5, s3, 0xffffffc0
	s_or_b32 s9, s97, 0x4000000
	s_or_b32 s10, s97, 0x6000000
	s_lshl_b64 s[0:1], s[0:1], 15
	v_readlane_b32 s3, v249, 48
	s_add_u32 s14, s3, s0
	v_readlane_b32 s3, v249, 49
	s_addc_u32 s15, s3, s1
	s_lshr_b32 s73, s4, 6
	s_lshl_b32 s2, s2, 2
	s_add_u32 s7, s14, s2
	v_or_b32_e32 v12, s5, v134
	s_addc_u32 s8, s15, 0
	s_lshl_b64 s[2:3], s[76:77], 2
	v_add_u32_e32 v0, s6, v12
	s_add_u32 s2, s7, s2
	v_ashrrev_i32_e32 v13, 3, v0
	v_and_b32_e32 v0, -8, v0
	s_addc_u32 s3, s8, s3
	v_lshlrev_b32_e32 v135, 2, v133
	v_sub_u32_e32 v14, v12, v0
	v_lshrrev_b32_e32 v0, 1, v13
	global_load_dword v3, v135, s[2:3]
	v_bitop3_b32 v15, v0, 7, v222 bitop3:0x48
	s_mov_b32 s2, 0x1ffffff8
	v_and_or_b32 v0, v14, s2, v15
	v_lshlrev_b32_e32 v0, 3, v0
	v_add_lshl_u32 v5, v13, s12, 10
	s_waitcnt lgkmcnt(0)
	v_add3_u32 v4, s9, v5, v0
	v_add_u32_e32 v0, 0x200, v12
	v_ashrrev_i32_e32 v6, 31, v0
	v_lshrrev_b32_e32 v6, 29, v6
	v_add_u32_e32 v6, v0, v6
	v_lshlrev_b32_e32 v8, 1, v13
	v_ashrrev_i32_e32 v16, 3, v6
	v_bitop3_b32 v8, v14, v8, 4 bitop3:0x78
	v_and_b32_e32 v17, -8, v6
	v_lshrrev_b32_e32 v6, 1, v16
	v_lshlrev_b32_e32 v19, 3, v8
	v_sub_u32_e32 v0, v0, v17
	v_bitop3_b32 v18, v6, 7, v222 bitop3:0x48
	v_add3_u32 v8, s10, v19, v5
	v_lshlrev_b32_e32 v5, 1, v16
	v_and_or_b32 v6, v0, s2, v18
	v_bitop3_b32 v0, v0, v5, 4 bitop3:0x78
	s_lshl_b32 s33, s71, 10
	v_lshlrev_b32_e32 v6, 3, v6
	v_writelane_b32 v248, s12, 7
	v_lshlrev_b32_e32 v20, 3, v0
	s_add_i32 s76, s33, 0
	v_add_lshl_u32 v7, v16, s12, 10
	v_mov_b32_e32 v5, v1
	v_add3_u32 v6, s9, v7, v6
	v_add3_u32 v10, s10, v20, v7
	v_lshl_add_u64 v[4:5], v[4:5], 1, s[84:85]
	s_mov_b32 m0, s76
	v_mov_b32_e32 v7, v1
	global_load_lds_dwordx4 v[4:5], off
	v_lshlrev_b32_e32 v4, 1, v6
	s_add_i32 m0, s76, 0x2000
	v_mov_b32_e32 v9, v1
	global_load_lds_dwordx4 v4, s[84:85]
	s_add_i32 m0, s76, 0x4000
	v_lshlrev_b32_e32 v4, 1, v8
	v_mov_b32_e32 v11, v1
	s_lshl_b32 s92, s71, 9
	v_lshlrev_b32_e32 v0, 2, v134
	global_load_lds_dwordx4 v4, s[84:85]
	v_lshlrev_b32_e32 v4, 1, v10
	s_add_i32 m0, s76, 0x6000
	s_add_i32 s2, s92, 0
	v_readlane_b32 s67, v249, 63
	v_writelane_b32 v249, s10, 48
	v_lshl_add_u64 v[106:107], s[14:15], 0, v[0:1]
	global_load_lds_dwordx4 v4, s[84:85]
	s_add_i32 m0, s2, 0x8000
	s_mov_b64 s[78:79], 0x100
	v_writelane_b32 v249, s14, 49
	v_lshl_add_u64 v[108:109], v[106:107], 0, s[78:79]
	v_lshlrev_b32_e32 v6, 7, v133
	v_mov_b32_e32 v5, 0x3f80
	v_cmp_eq_u32_e32 vcc, 0, v133
	v_lshlrev_b32_e32 v132, 2, v2
	global_load_lds_dword v0, s[14:15]
	s_add_i32 m0, s2, 0x8100
	s_lshl_b32 s2, s64, 2
	global_load_lds_dword v[108:109], off
	s_add_i32 s2, s2, 0
	s_add_i32 s2, s2, 0x1b000
	v_mov_b32_e32 v4, s2
	s_waitcnt vmcnt(0) lgkmcnt(0)
	s_barrier
	s_waitcnt vmcnt(0)
	ds_read_b32 v4, v4
	v_cndmask_b32_e32 v5, 0, v5, vcc
	s_mov_b32 s2, 0x5040100
	v_perm_b32 v84, v5, v5, s2
	s_and_b32 s2, s4, 0x7fffffc0
	s_waitcnt lgkmcnt(0)
	v_add_f32_e32 v110, v3, v4
	v_lshrrev_b32_e32 v3, 1, v222
	v_bfe_u32 v4, v222, 1, 3
	v_bitop3_b32 v3, v2, v3, 7 bitop3:0x78
	v_lshl_or_b32 v125, v3, 4, v6
	v_bitop3_b32 v3, v2, v4, 2 bitop3:0x36
	v_lshl_or_b32 v126, v3, 4, v6
	v_bitop3_b32 v3, v2, v4, 4 bitop3:0x36
	v_lshl_or_b32 v127, v3, 4, v6
	v_bitop3_b32 v3, v2, v4, 6 bitop3:0x36
	v_lshl_or_b32 v128, v3, 4, v6
	v_lshlrev_b32_e32 v3, 5, v222
	v_lshrrev_b32_e32 v4, 3, v222
	v_bfe_u32 v6, v222, 1, 1
	v_and_b32_e32 v3, 0x180, v3
	v_and_or_b32 v4, v4, 2, v6
	v_lshlrev_b32_e32 v6, 3, v222
	v_lshl_or_b32 v3, v2, 9, v3
	v_lshlrev_b32_e32 v4, 4, v4
	v_and_b32_e32 v7, 8, v6
	v_or_b32_e32 v2, s2, v132
	v_or3_b32 v129, v3, v4, v7
	v_or_b32_e32 v51, s4, v133
	v_or_b32_e32 v3, 32, v2
	v_writelane_b32 v248, s13, 8
	v_cmp_gt_u32_e64 s[4:5], v3, v51
	v_or_b32_e32 v3, 33, v2
	v_writelane_b32 v248, s9, 9
	v_cmp_gt_u32_e64 s[8:9], v3, v51
	v_or_b32_e32 v3, 2, v2
	v_cmp_gt_u32_e64 s[10:11], v3, v51
	v_or_b32_e32 v3, 34, v2
	v_cmp_gt_u32_e64 s[12:13], v3, v51
	v_or_b32_e32 v3, 3, v2
	v_writelane_b32 v249, s15, 50
	v_cmp_gt_u32_e64 s[14:15], v3, v51
	v_or_b32_e32 v3, 35, v2
	v_cmp_gt_u32_e64 s[16:17], v3, v51
	v_or_b32_e32 v3, 8, v2
	v_cmp_gt_u32_e64 s[18:19], v3, v51
	v_or_b32_e32 v3, 40, v2
	v_cmp_gt_u32_e64 s[20:21], v3, v51
	v_or_b32_e32 v3, 9, v2
	v_cmp_gt_u32_e64 s[22:23], v3, v51
	v_or_b32_e32 v3, 41, v2
	v_cmp_gt_u32_e64 s[24:25], v3, v51
	v_or_b32_e32 v3, 10, v2
	v_cmp_gt_u32_e64 s[26:27], v3, v51
	v_or_b32_e32 v3, 42, v2
	v_cmp_gt_u32_e64 s[28:29], v3, v51
	v_or_b32_e32 v3, 11, v2
	v_cmp_gt_u32_e64 s[30:31], v3, v51
	v_or_b32_e32 v3, 43, v2
	v_cmp_gt_u32_e64 s[34:35], v3, v51
	v_or_b32_e32 v3, 16, v2
	v_cmp_gt_u32_e64 s[36:37], v3, v51
	v_or_b32_e32 v3, 48, v2
	v_cmp_gt_u32_e64 s[38:39], v3, v51
	v_or_b32_e32 v3, 17, v2
	v_cmp_gt_u32_e64 s[40:41], v3, v51
	v_or_b32_e32 v3, 49, v2
	v_cmp_gt_u32_e64 s[42:43], v3, v51
	v_or_b32_e32 v3, 18, v2
	v_cmp_gt_u32_e64 s[44:45], v3, v51
	v_or_b32_e32 v3, 50, v2
	v_cmp_gt_u32_e64 s[46:47], v3, v51
	v_or_b32_e32 v3, 19, v2
	v_cmp_gt_u32_e64 s[48:49], v3, v51
	v_or_b32_e32 v3, 51, v2
	v_cmp_gt_u32_e64 s[50:51], v3, v51
	v_or_b32_e32 v3, 24, v2
	v_cmp_gt_u32_e64 s[52:53], v3, v51
	v_or_b32_e32 v3, 56, v2
	v_cmp_gt_u32_e64 s[54:55], v3, v51
	v_or_b32_e32 v3, 25, v2
	v_cmp_gt_u32_e64 s[56:57], v3, v51
	v_or_b32_e32 v3, 57, v2
	v_cmp_gt_u32_e64 s[58:59], v3, v51
	v_or_b32_e32 v3, 26, v2
	v_cmp_gt_u32_e64 s[60:61], v3, v51
	v_or_b32_e32 v3, 58, v2
	s_lshl_b32 s66, s66, 23
	v_sub_u32_e32 v4, v12, v17
	v_mov_b32_e32 v5, 0x1000
	v_cmp_gt_u32_e64 s[2:3], v2, v51
	v_cmp_lt_u32_e64 s[6:7], v2, v51
	v_cmp_gt_u32_e64 s[62:63], v3, v51
	v_or_b32_e32 v52, 27, v2
	v_or_b32_e32 v53, 59, v2
	v_lshl_add_u32 v2, v16, 10, s66
	v_lshl_add_u32 v3, v13, 10, s66
	v_lshl_add_u32 v4, v4, 3, v5
	v_or_b32_e32 v2, s97, v2
	s_mov_b32 s65, 0x6020000
	v_or_b32_e32 v3, s97, v3
	v_and_b32_e32 v4, 0xffffffc0, v4
	v_add3_u32 v111, v2, v20, s65
	v_add3_u32 v112, v3, v19, s65
	v_add_u32_e32 v2, v2, v4
	v_lshlrev_b32_e32 v4, 3, v18
	s_mov_b32 s65, 0x4020000
	s_add_i32 s93, s73, -1
	v_add3_u32 v113, v2, v4, s65
	v_lshlrev_b32_e32 v2, 3, v14
	v_and_b32_e32 v2, 0xffffffc0, v2
	s_add_u32 s0, s84, s0
	v_add_u32_e32 v2, v3, v2
	v_lshlrev_b32_e32 v3, 3, v15
	s_addc_u32 s1, s85, s1
	v_add3_u32 v114, v2, v3, s65
	v_lshl_add_u64 v[2:3], s[0:1], 0, v[0:1]
	s_mov_b64 s[0:1], 0x400200
	v_and_b32_e32 v130, 64, v6
	v_bitop3_b32 v131, v6, 64, v6 bitop3:0xc
	v_lshl_add_u64 v[104:105], v[2:3], 0, s[0:1]
	v_mov_b32_e32 v2, v1
	v_mov_b32_e32 v3, v1
	v_mov_b32_e32 v4, v1
	v_mov_b32_e32 v5, v1
	v_mov_b32_e32 v6, v1
	v_mov_b32_e32 v7, v1
	v_mov_b32_e32 v8, v1
	v_mov_b32_e32 v10, v1
	v_mov_b32_e32 v12, v1
	v_mov_b32_e32 v13, v1
	v_mov_b32_e32 v14, v1
	v_mov_b32_e32 v15, v1
	v_mov_b32_e32 v16, v1
	v_mov_b32_e32 v17, v1
	v_mov_b32_e32 v18, v1
	v_mov_b32_e32 v19, v1
	v_mov_b32_e32 v20, v1
	v_mov_b32_e32 v21, v1
	v_mov_b32_e32 v22, v1
	v_mov_b32_e32 v23, v1
	v_mov_b32_e32 v24, v1
	v_mov_b32_e32 v25, v1
	v_mov_b32_e32 v26, v1
	v_mov_b32_e32 v27, v1
	v_mov_b32_e32 v28, v1
	v_mov_b32_e32 v29, v1
	v_mov_b32_e32 v30, v1
	v_mov_b32_e32 v31, v1
	s_lshl_b32 s94, s64, 18
	v_mov_b32_e32 v0, v1
	v_mov_b64_e32 v[32:33], v[30:31]
	v_mov_b32_e32 v85, v84
	v_mov_b32_e32 v86, v84
	v_mov_b32_e32 v87, v84
	v_writelane_b32 v248, s66, 0
	s_add_i32 s94, s94, 0x40000
	v_mov_b32_e32 v34, v1
	v_mov_b32_e32 v35, v1
	v_mov_b32_e32 v36, v1
	v_mov_b32_e32 v37, v1
	v_mov_b32_e32 v38, v1
	v_mov_b32_e32 v39, v1
	v_mov_b32_e32 v40, v1
	v_mov_b32_e32 v41, v1
	v_mov_b32_e32 v42, v1
	v_mov_b32_e32 v43, v1
	v_mov_b32_e32 v44, v1
	v_mov_b32_e32 v45, v1
	v_mov_b32_e32 v46, v1
	v_mov_b32_e32 v47, v1
	v_mov_b32_e32 v48, v1
	v_mov_b32_e32 v49, v1
	s_mov_b32 s96, 0x9000
	s_mov_b32 s95, 0x41800000
	v_mov_b32_e32 v115, 0xf149f2ca
	v_mov_b64_e32 v[82:83], v[104:105]
	s_mov_b32 s70, s77
	v_mov_b32_e32 v116, 0
	s_mov_b32 s0, s77
	v_mov_b64_e32 v[30:31], v[28:29]
	v_mov_b64_e32 v[28:29], v[26:27]
	v_mov_b64_e32 v[26:27], v[24:25]
	v_mov_b64_e32 v[24:25], v[22:23]
	v_mov_b64_e32 v[22:23], v[20:21]
	v_mov_b64_e32 v[20:21], v[18:19]
	v_mov_b64_e32 v[18:19], v[16:17]
	v_mov_b64_e32 v[16:17], v[14:15]
	v_mov_b64_e32 v[14:15], v[12:13]
	v_mov_b64_e32 v[12:13], v[10:11]
	v_mov_b64_e32 v[10:11], v[8:9]
	v_mov_b64_e32 v[8:9], v[6:7]
	v_mov_b64_e32 v[6:7], v[4:5]
	v_mov_b64_e32 v[4:5], v[2:3]
	v_mov_b64_e32 v[2:3], v[0:1]
	s_mov_b32 s1, s77
	v_cmp_gt_u32_e64 s[64:65], v52, v51
	v_cmp_gt_u32_e64 s[66:67], v53, v51
	s_add_i32 s90, s1, 1
	s_cmp_ge_u32 s90, s72
	s_cbranch_scc1 .LBB0_750
.LBB0_749:
	s_add_i32 s68, s76, s96
	v_add_u32_e32 v0, s70, v114
	v_lshlrev_b32_e32 v118, 1, v0
	s_mov_b32 m0, s68
	v_add_u32_e32 v0, s70, v113
	global_load_lds_dwordx4 v118, s[84:85]
	s_add_i32 m0, s68, 0x2000
	s_add_i32 s68, s96, 0
	v_lshlrev_b32_e32 v118, 1, v0
	s_add_i32 s69, s68, s33
	v_add_u32_e32 v0, s70, v112
	global_load_lds_dwordx4 v118, s[84:85]
	s_add_i32 m0, s69, 0x4000
	v_lshlrev_b32_e32 v118, 1, v0
	v_add_u32_e32 v0, s70, v111
	global_load_lds_dwordx4 v118, s[84:85]
	v_lshlrev_b32_e32 v118, 1, v0
	s_add_i32 m0, s69, 0x6000
	s_add_i32 s68, s68, s92
	global_load_lds_dwordx4 v118, s[84:85]
	s_add_i32 m0, s68, 0x8000
	v_lshl_add_u64 v[118:119], v[82:83], 0, s[78:79]
	global_load_lds_dword v[82:83], off
	s_add_i32 m0, s68, 0x8100
	s_nop 0
	global_load_lds_dword v[118:119], off

.LBB0_776:
	s_and_b32 s5, s4, 0xffffffc0
	v_or_b32_e32 v4, s5, v134
	v_add_u32_e32 v8, 0x200, v4
	v_ashrrev_i32_e32 v9, 31, v8
	v_lshrrev_b32_e32 v9, 29, v9
	v_add_u32_e32 v9, v8, v9
	s_ashr_i32 s4, s4, 31
	v_ashrrev_i32_e32 v10, 3, v9
	v_and_b32_e32 v9, -8, v9
	s_lshr_b32 s4, s4, 29
	v_sub_u32_e32 v13, v8, v9
	v_lshrrev_b32_e32 v8, 1, v10
	v_add_u32_e32 v2, s4, v4
	s_mov_b32 s4, 0x1ffffff8
	v_bitop3_b32 v8, v8, 7, v222 bitop3:0x48
	v_ashrrev_i32_e32 v7, 3, v2
	v_and_b32_e32 v2, -8, v2
	v_and_or_b32 v11, v13, s4, v8
	v_sub_u32_e32 v6, v4, v2
	v_lshrrev_b32_e32 v2, 1, v7
	v_readlane_b32 s5, v248, 9
	v_lshlrev_b32_e32 v11, 3, v11
	v_add_lshl_u32 v15, v10, s8, 10
	s_waitcnt lgkmcnt(0)
	v_bitop3_b32 v5, v2, 7, v222 bitop3:0x48
	v_add3_u32 v14, s5, v15, v11
	v_lshlrev_b32_e32 v11, 1, v7
	s_add_i32 s1, s3, 0x100
	v_and_or_b32 v2, v6, s4, v5
	v_bitop3_b32 v11, v6, v11, 4 bitop3:0x78
	v_lshlrev_b32_e32 v2, 3, v2
	v_add_lshl_u32 v12, v7, s8, 10
	s_lshr_b32 s92, s1, 7
	v_lshlrev_b32_e32 v11, 3, v11
	v_readlane_b32 s1, v249, 48
	v_add3_u32 v2, s5, v12, v2
	s_add_i32 s0, s76, s3
	v_add3_u32 v16, s1, v11, v12
	v_lshlrev_b32_e32 v12, 1, v10
	v_bitop3_b32 v12, v13, v12, 4 bitop3:0x78
	v_lshlrev_b32_e32 v12, 3, v12
	v_add3_u32 v18, s1, v12, v15
	s_lshr_b32 s71, s0, 6
	s_lshl_b32 s1, s3, 2
	v_readlane_b32 s4, v249, 49
	v_readlane_b32 s5, v249, 50
	s_add_u32 s1, s4, s1
	s_addc_u32 s3, s5, 0
	s_lshl_b64 s[4:5], s[76:77], 2
	s_add_u32 s4, s1, s4
	s_addc_u32 s5, s3, s5
	s_lshl_b32 s93, s96, 10
	s_add_i32 s72, s93, 0
	v_lshlrev_b32_e32 v20, 1, v2
	s_mov_b32 m0, s72
	v_mov_b32_e32 v15, v3
	global_load_lds_dwordx4 v20, s[84:85]
	v_lshl_add_u64 v[14:15], v[14:15], 1, s[84:85]
	s_add_i32 m0, s72, 0x2000
	v_mov_b32_e32 v17, v3
	global_load_lds_dwordx4 v[14:15], off
	s_add_i32 m0, s72, 0x4000
	v_lshlrev_b32_e32 v14, 1, v16
	v_mov_b32_e32 v19, v3
	s_lshl_b32 s73, s96, 9
	global_load_lds_dwordx4 v14, s[84:85]
	v_lshlrev_b32_e32 v14, 1, v18
	s_add_i32 m0, s72, 0x6000
	s_add_i32 s1, s73, 0
	global_load_lds_dwordx4 v14, s[84:85]
	s_add_i32 m0, s1, 0x8000
	global_load_dword v2, v135, s[4:5]
	v_sub_u32_e32 v4, v4, v9
	global_load_lds_dword v[106:107], off
	s_add_i32 m0, s1, 0x8100
	s_lshl_b32 s1, s2, 2
	global_load_lds_dword v[108:109], off
	s_add_i32 s1, s1, 0
	s_add_i32 s1, s1, 0x1b000
	v_mov_b32_e32 v13, s1
	s_waitcnt vmcnt(0) lgkmcnt(0)
	s_barrier
	s_waitcnt vmcnt(0)
	ds_read_b32 v13, v13
	v_readlane_b32 s1, v248, 6
	v_mov_b32_e32 v9, 0x1000
	v_lshl_add_u32 v4, v4, 3, v9
	v_and_b32_e32 v4, 0xffffffc0, v4
	s_waitcnt lgkmcnt(0)
	v_add_f32_e32 v113, v2, v13
	v_or_b32_e32 v2, s0, v133
	s_and_b32 s0, s0, 0x7fffffc0
	v_or_b32_e32 v13, s0, v132
	v_or_b32_e32 v14, 32, v13
	v_cmp_gt_u32_e64 s[4:5], v14, v2
	v_or_b32_e32 v14, 33, v13
	v_cmp_gt_u32_e64 s[8:9], v14, v2
	v_or_b32_e32 v14, 2, v13
	v_cmp_gt_u32_e64 s[10:11], v14, v2
	v_or_b32_e32 v14, 34, v13
	v_cmp_gt_u32_e64 s[12:13], v14, v2
	v_or_b32_e32 v14, 3, v13
	v_cmp_gt_u32_e64 s[14:15], v14, v2
	v_or_b32_e32 v14, 35, v13
	v_cmp_gt_u32_e64 s[16:17], v14, v2
	v_or_b32_e32 v14, 8, v13
	v_cmp_gt_u32_e64 s[18:19], v14, v2
	v_or_b32_e32 v14, 40, v13
	v_cmp_gt_u32_e64 s[20:21], v14, v2
	v_or_b32_e32 v14, 9, v13
	v_cmp_gt_u32_e64 s[22:23], v14, v2
	v_or_b32_e32 v14, 41, v13
	v_cmp_gt_u32_e64 s[24:25], v14, v2
	v_or_b32_e32 v14, 10, v13
	v_cmp_gt_u32_e64 s[26:27], v14, v2
	v_or_b32_e32 v14, 42, v13
	v_cmp_gt_u32_e64 s[28:29], v14, v2
	v_or_b32_e32 v14, 11, v13
	v_cmp_gt_u32_e64 s[30:31], v14, v2
	v_or_b32_e32 v14, 43, v13
	v_cmp_gt_u32_e64 s[34:35], v14, v2
	v_or_b32_e32 v14, 16, v13
	v_cmp_gt_u32_e64 s[36:37], v14, v2
	v_or_b32_e32 v14, 48, v13
	v_cmp_gt_u32_e64 s[38:39], v14, v2
	v_or_b32_e32 v14, 17, v13
	v_cmp_gt_u32_e64 s[40:41], v14, v2
	v_or_b32_e32 v14, 49, v13
	v_cmp_gt_u32_e64 s[42:43], v14, v2
	v_or_b32_e32 v14, 18, v13
	v_cmp_gt_u32_e64 s[44:45], v14, v2
	v_or_b32_e32 v14, 50, v13
	v_cmp_gt_u32_e64 s[46:47], v14, v2
	v_or_b32_e32 v14, 19, v13
	v_cmp_gt_u32_e64 s[48:49], v14, v2
	v_or_b32_e32 v14, 51, v13
	v_cmp_gt_u32_e64 s[50:51], v14, v2
	v_or_b32_e32 v14, 24, v13
	v_cmp_gt_u32_e64 s[52:53], v14, v2
	v_or_b32_e32 v14, 56, v13
	v_cmp_gt_u32_e64 s[54:55], v14, v2
	v_or_b32_e32 v14, 25, v13
	s_lshl_b32 s0, s1, 8
	v_cmp_gt_u32_e64 s[56:57], v14, v2
	v_or_b32_e32 v14, 57, v13
	v_writelane_b32 v249, s0, 58
	s_add_i32 s0, s0, s76
	v_cmp_gt_u32_e64 s[58:59], v14, v2
	v_or_b32_e32 v14, 26, v13
	s_addk_i32 s0, 0x1800
	v_cmp_gt_u32_e64 s[60:61], v14, v2
	v_or_b32_e32 v14, 58, v13
	s_lshr_b32 s33, s0, 6
	v_readlane_b32 s0, v248, 0
	v_cmp_gt_u32_e64 s[2:3], v13, v2
	v_cmp_lt_u32_e64 s[6:7], v13, v2
	v_cmp_gt_u32_e64 s[62:63], v14, v2
	v_or_b32_e32 v14, 27, v13
	v_or_b32_e32 v13, 59, v13
	s_add_i32 s97, s97, s0
	v_cmp_gt_u32_e64 s[64:65], v14, v2
	v_cmp_gt_u32_e64 s[66:67], v13, v2
	v_lshl_add_u32 v2, v10, 10, s97
	s_mov_b32 s0, 0x6020000
	v_lshl_add_u32 v7, v7, 10, s97
	v_add3_u32 v115, v2, v12, s0
	v_add3_u32 v117, v7, v11, s0
	v_add_u32_e32 v2, v2, v4
	v_lshlrev_b32_e32 v4, 3, v8
	s_mov_b32 s0, 0x4020000
	v_add3_u32 v121, v2, v4, s0
	v_lshlrev_b32_e32 v2, 3, v6
	v_and_b32_e32 v2, 0xffffffc0, v2
	v_add_u32_e32 v2, v7, v2
	v_lshlrev_b32_e32 v4, 3, v5
	v_add3_u32 v122, v2, v4, s0
	v_mov_b32_e32 v4, v3
	v_mov_b32_e32 v5, v3
	v_mov_b32_e32 v6, v3
	v_mov_b32_e32 v7, v3
	v_mov_b32_e32 v8, v3
	v_mov_b32_e32 v9, v3
	v_mov_b32_e32 v10, v3
	v_mov_b32_e32 v11, v3
	v_mov_b32_e32 v12, v3
	v_mov_b32_e32 v13, v3
	v_mov_b32_e32 v14, v3
	v_mov_b32_e32 v15, v3
	v_mov_b32_e32 v16, v3
	v_mov_b32_e32 v18, v3
	v_mov_b32_e32 v20, v3
	v_mov_b32_e32 v21, v3
	v_mov_b32_e32 v22, v3
	v_mov_b32_e32 v23, v3
	v_mov_b32_e32 v24, v3
	v_mov_b32_e32 v25, v3
	v_mov_b32_e32 v26, v3
	v_mov_b32_e32 v27, v3
	v_mov_b32_e32 v28, v3
	v_mov_b32_e32 v29, v3
	v_mov_b32_e32 v30, v3
	v_mov_b32_e32 v31, v3
	v_mov_b32_e32 v32, v3
	v_mov_b32_e32 v33, v3
	s_lshl_b32 s0, s1, 18
	v_mov_b32_e32 v2, v3
	v_mov_b64_e32 v[34:35], v[32:33]
	s_add_i32 s76, s33, -1
	v_writelane_b32 v248, s0, 0
	s_add_i32 s70, s0, 0x640000
	v_mov_b32_e32 v36, v3
	v_mov_b32_e32 v37, v3
	v_mov_b32_e32 v38, v3
	v_mov_b32_e32 v39, v3
	v_mov_b32_e32 v40, v3
	v_mov_b32_e32 v41, v3
	v_mov_b32_e32 v42, v3
	v_mov_b32_e32 v43, v3
	v_mov_b32_e32 v44, v3
	v_mov_b32_e32 v45, v3
	v_mov_b32_e32 v46, v3
	v_mov_b32_e32 v47, v3
	v_mov_b32_e32 v48, v3
	v_mov_b32_e32 v49, v3
	v_mov_b32_e32 v50, v3
	v_mov_b32_e32 v51, v3
	s_mov_b32 s94, 0x41800000
	v_mov_b32_e32 v123, 0xf149f2ca
	v_mov_b64_e32 v[118:119], v[104:105]
	s_mov_b32 s95, s77
	v_mov_b32_e32 v137, 0
	s_mov_b32 s0, s77
	s_mov_b32 s1, s77
	v_mov_b64_e32 v[32:33], v[30:31]
	v_mov_b64_e32 v[30:31], v[28:29]
	v_mov_b64_e32 v[28:29], v[26:27]
	v_mov_b64_e32 v[26:27], v[24:25]
	v_mov_b64_e32 v[24:25], v[22:23]
	v_mov_b64_e32 v[22:23], v[20:21]
	v_mov_b64_e32 v[20:21], v[18:19]
	v_mov_b64_e32 v[18:19], v[16:17]
	v_mov_b64_e32 v[16:17], v[14:15]
	v_mov_b64_e32 v[14:15], v[12:13]
	v_mov_b64_e32 v[12:13], v[10:11]
	v_mov_b64_e32 v[10:11], v[8:9]
	v_mov_b64_e32 v[8:9], v[6:7]
	v_mov_b64_e32 v[6:7], v[4:5]
	v_mov_b64_e32 v[4:5], v[2:3]
	s_add_i32 s90, s1, 1
	s_cmp_ge_u32 s90, s92
	s_cbranch_scc1 .LBB0_778
.LBB0_777:
	s_add_i32 s68, s72, s75
	v_add_u32_e32 v2, s95, v122
	v_lshlrev_b32_e32 v138, 1, v2
	s_mov_b32 m0, s68
	v_add_u32_e32 v2, s95, v121
	global_load_lds_dwordx4 v138, s[84:85]
	s_add_i32 m0, s68, 0x2000
	s_add_i32 s68, s75, 0
	v_lshlrev_b32_e32 v138, 1, v2
	s_add_i32 s69, s68, s93
	v_add_u32_e32 v2, s95, v117
	global_load_lds_dwordx4 v138, s[84:85]
	s_add_i32 m0, s69, 0x4000
	v_lshlrev_b32_e32 v138, 1, v2
	v_add_u32_e32 v2, s95, v115
	global_load_lds_dwordx4 v138, s[84:85]
	v_lshlrev_b32_e32 v138, 1, v2
	s_add_i32 m0, s69, 0x6000
	s_add_i32 s91, s68, s73
	global_load_lds_dwordx4 v138, s[84:85]
	s_add_i32 m0, s91, 0x8000
	s_mov_b64 s[68:69], 0x100
	global_load_lds_dword v[118:119], off
	v_lshl_add_u64 v[138:139], v[118:119], 0, s[68:69]
	s_add_i32 m0, s91, 0x8100
	s_nop 0
	global_load_lds_dword v[138:139], off

.LBB0_805:
	s_add_i32 s68, s76, s71
	v_add_u32_e32 v2, s90, v119
	v_lshlrev_b32_e32 v138, 1, v2
	s_mov_b32 m0, s68
	v_add_u32_e32 v2, s90, v117
	global_load_lds_dwordx4 v138, s[84:85]
	s_add_i32 m0, s68, 0x2000
	s_add_i32 s68, s71, 0
	v_lshlrev_b32_e32 v138, 1, v2
	s_add_i32 s69, s68, s33
	v_add_u32_e32 v2, s90, v115
	global_load_lds_dwordx4 v138, s[84:85]
	s_add_i32 m0, s69, 0x4000
	v_lshlrev_b32_e32 v138, 1, v2
	v_add_u32_e32 v2, s90, v113
	global_load_lds_dwordx4 v138, s[84:85]
	v_lshlrev_b32_e32 v138, 1, v2
	s_add_i32 m0, s69, 0x6000
	s_add_i32 s95, s68, s75
	global_load_lds_dwordx4 v138, s[84:85]
	s_add_i32 m0, s95, 0x8000
	s_mov_b64 s[68:69], 0x100
	global_load_lds_dword v[122:123], off
	v_lshl_add_u64 v[138:139], v[122:123], 0, s[68:69]
	s_add_i32 m0, s95, 0x8100
	s_nop 0
	global_load_lds_dword v[138:139], off

.LBB0_833:
	s_add_i32 s68, s92, s71
	v_add_u32_e32 v2, s96, v119
	v_lshlrev_b32_e32 v138, 1, v2
	s_mov_b32 m0, s68
	v_add_u32_e32 v2, s96, v117
	global_load_lds_dwordx4 v138, s[84:85]
	s_add_i32 m0, s68, 0x2000
	s_add_i32 s68, s71, 0
	v_lshlrev_b32_e32 v138, 1, v2
	s_add_i32 s69, s68, s33
	v_add_u32_e32 v2, s96, v115
	global_load_lds_dwordx4 v138, s[84:85]
	s_add_i32 m0, s69, 0x4000
	v_lshlrev_b32_e32 v138, 1, v2
	v_add_u32_e32 v2, s96, v113
	global_load_lds_dwordx4 v138, s[84:85]
	v_lshlrev_b32_e32 v138, 1, v2
	s_add_i32 m0, s69, 0x6000
	s_add_i32 s91, s68, s75
	global_load_lds_dwordx4 v138, s[84:85]
	s_add_i32 m0, s91, 0x8000
	s_mov_b64 s[68:69], 0x100
	global_load_lds_dword v[122:123], off
	v_lshl_add_u64 v[138:139], v[122:123], 0, s[68:69]
	s_add_i32 m0, s91, 0x8100
	s_nop 0
	global_load_lds_dword v[138:139], off

.LBB0_945:
	s_add_i32 s93, s75, s69
	v_add_u32_e32 v0, s90, v108
	v_lshlrev_b32_e32 v122, 1, v0
	s_mov_b32 m0, s93
	v_add_u32_e32 v0, s90, v107
	global_load_lds_dwordx4 v122, s[84:85]
	s_add_i32 m0, s93, 0x2000
	s_add_i32 s93, s69, 0
	v_lshlrev_b32_e32 v122, 1, v0
	s_add_i32 s94, s93, s72
	v_add_u32_e32 v0, s90, v106
	global_load_lds_dwordx4 v122, s[84:85]
	s_add_i32 m0, s94, 0x4000
	v_lshlrev_b32_e32 v122, 1, v0
	v_add_u32_e32 v0, s90, v83
	global_load_lds_dwordx4 v122, s[84:85]
	v_lshlrev_b32_e32 v122, 1, v0
	s_add_i32 m0, s94, 0x6000
	s_add_i32 s93, s93, s73
	global_load_lds_dwordx4 v122, s[84:85]
	s_add_i32 m0, s93, 0x8000
	s_mov_b64 s[94:95], 0x100
	global_load_lds_dword v[104:105], off
	v_lshl_add_u64 v[122:123], v[104:105], 0, s[94:95]
	s_add_i32 m0, s93, 0x8100
	s_nop 0
	global_load_lds_dword v[122:123], off
